# PanelRms row-statistics exchange (P2 x2, P8 x2, P11): readers poll the slot data (preset to 0xFFFFFFFF in P0) instead of store+vmcnt(0)+counter atomic+wave-0 counter spin+buffer_inv; same sc1 stores/l
# speedup vs baseline: 1.0053x; 1.0053x over previous
; #define GAS __attribute__((address_space(1)))
; #define LAS __attribute__((address_space(3)))
; __global__ void __launch_bounds__(NWAVES * 64, 2) hybrid_fwd(const Args A) {
;     ...
;     const int lo = A.ph_lo, hi = A.ph_hi;
;     cg::grid_group grid = cg::this_grid();
;     volatile LAS unsigned* MISC = (volatile LAS unsigned*)(F.lds + L_MISC);
;     if (F.tid < 16) MISC[F.tid] = 0u;
;     __syncthreads();
;     XcdBarrier bar; bar.bar = F.ctl + CW_BAR; bar.x = 0; bar.st = nullptr;
;     if (hi - lo > 1) {
;         if (blockIdx.x == 0) { GAS v4u* z = (GAS v4u*)(F.ws + WS_CTL); for (int i = F.tid; i < (int)(CTL_ZERO_BYTES / 16); i += NWAVES * 64) if (i < (int)(WS_PRM / 16) || i >= (int)((CW_SEAM * 4) / 16)) z[i] = (v4u){0u, 0u, 0u, 0u}; }
;         grid.sync();
.LBB0_2:
	s_load_dwordx4 s[36:39], s[72:73], 0x0
	s_load_dwordx2 s[34:35], s[72:73], 0x10
	s_load_dwordx4 s[84:87], s[72:73], 0xf8
	s_load_dwordx2 s[0:1], s[2:3], 0x4
	s_and_b32 s70, s79, 0xffffffc0
	v_add_u32_e32 v210, s70, v208
	v_cmp_gt_i32_e32 vcc, 16, v210
	s_waitcnt lgkmcnt(0)
	v_writelane_b32 v254, s0, 4
	s_nop 1
	v_writelane_b32 v254, s1, 5
	s_and_saveexec_b64 s[0:1], vcc
	v_lshl_add_u32 v2, v210, 2, 0
	v_add_u32_e32 v2, 0x25700, v2
	v_mov_b32_e32 v3, 0
	ds_write_b32 v2, v3
	s_or_b64 exec, exec, s[0:1]
	s_lshl_b32 s0, s82, 9
	v_add_u32_e32 v2, s0, v210
	s_lshl_b32 s4, s77, 9
	v_mov_b32_e32 v8, s4
	s_add_u32 s4, s86, 0x2d00000
	s_addc_u32 s5, s87, 0
	v_mov_b32_e32 v4, -1
	v_mov_b32_e32 v5, -1
	v_mov_b32_e32 v6, -1
	v_mov_b32_e32 v7, -1
	s_mov_b64 s[0:1], exec
.Lprs_init:
	v_cmp_gt_u32_e32 vcc, 0x14000, v2
	s_and_b64 exec, exec, vcc
	s_cbranch_execz .Lprs_init_done
	v_lshlrev_b32_e32 v10, 4, v2
	v_mov_b32_e32 v11, 0
	v_lshl_add_u64 v[10:11], s[4:5], 0, v[10:11]
	global_store_dwordx4 v[10:11], v[4:7], off sc1
	v_add_u32_e32 v2, v2, v8
	s_branch .Lprs_init
.Lprs_init_done:
	s_mov_b64 exec, s[0:1]
	s_add_u32 s0, s86, 0x4000
	s_addc_u32 s1, s87, 0
	v_writelane_b32 v254, s0, 6
	s_mov_b32 s5, 0
	s_waitcnt lgkmcnt(0)
	v_writelane_b32 v254, s1, 7
	s_load_dwordx2 s[0:1], s[72:73], 0x108
	s_barrier
	s_waitcnt lgkmcnt(0)
	s_sub_i32 s4, s1, s0
	s_cmp_gt_i32 s4, 1
	s_cselect_b64 s[0:1], -1, 0
	s_cmp_lt_i32 s4, 2
	s_mov_b32 s4, 0
	v_writelane_b32 v254, s4, 8
	s_cbranch_scc1 .LBB0_26
	s_cmp_eq_u32 s82, 0
	s_movk_i32 s6, 0x4000
	s_cselect_b64 s[4:5], -1, 0
	v_cmp_gt_i32_e32 vcc, s6, v210
	s_and_b64 s[6:7], s[4:5], vcc
	s_and_saveexec_b64 s[4:5], s[6:7]
	s_cbranch_execz .LBB0_10
	v_ashrrev_i32_e32 v211, 31, v210
	v_mov_b32_e32 v2, 0
	v_add_u32_e32 v8, 0xfffffe00, v210
	v_lshl_add_u64 v[6:7], v[210:211], 4, s[86:87]
	s_mov_b64 s[6:7], 0
	s_movk_i32 s12, 0xf000
	s_mov_b64 s[8:9], 0x2000
	s_movk_i32 s13, 0x3dff
	v_mov_b32_e32 v3, v2
	v_mov_b32_e32 v4, v2
	v_mov_b32_e32 v5, v2
	s_branch .LBB0_8

;     __device__ __forceinline__ void run(const f32x4 (&v)[2][2][4][2], const Unit& u, int wr, int wc, int fr, int fq, PG8_LAS unsigned char* lds, int wid, int lane) const {
;     ...
;             __hip_atomic_store(xbuf + ((size_t)(u.pm * BM + row) * 4 + u.pn), t, __ATOMIC_RELAXED, __HIP_MEMORY_SCOPE_AGENT);
;         }
;         asm volatile("s_waitcnt vmcnt(0)" ::: "memory");
.LBB0_779:
	s_or_b64 exec, exec, s[2:3]

;     __device__ __forceinline__ void run(const f32x4 (&v)[2][2][4][2], const Unit& u, int wr, int wc, int fr, int fq, PG8_LAS unsigned char* lds, int wid, int lane) const {
;     ...
;         if (lane == 0) __hip_atomic_fetch_add(cnt + 64 * u.pm, 1u, __ATOMIC_RELAXED, __HIP_MEMORY_SCOPE_AGENT);
	s_add_u32 s1, s86, 0x20000
	s_addc_u32 s14, s87, 0
	v_cmp_eq_u32_e64 s[8:9], 0, v192
	s_and_saveexec_b64 s[2:3], s[8:9]
	s_cbranch_execz .LBB0_782
	s_mov_b64 s[12:13], exec
	v_mbcnt_lo_u32_b32 v192, s12, 0
	v_mbcnt_hi_u32_b32 v192, s13, v192
	v_cmp_eq_u32_e32 vcc, 0, v192
	s_and_b64 s[18:19], exec, vcc
	s_mov_b64 exec, s[18:19]
	s_cbranch_execz .LBB0_782
	s_lshl_b32 s18, s20, 6
	s_ashr_i32 s19, s18, 31
	s_lshl_b64 s[18:19], s[18:19], 2
	s_add_u32 s18, s1, s18
	s_addc_u32 s19, s14, s19
	s_bcnt1_i32_b64 s12, s[12:13]
	v_mov_b32_e32 v192, 0
	s_waitcnt lgkmcnt(0)
	v_mov_b32_e32 v194, s12

;     __device__ __forceinline__ void run(const f32x4 (&v)[2][2][4][2], const Unit& u, int wr, int wc, int fr, int fq, PG8_LAS unsigned char* lds, int wid, int lane) const {
;     ...
;         if (wid == 0) {
;             unsigned spins = 0;
;             for (;;) {
;                 if ((unsigned)__builtin_amdgcn_readfirstlane(__hip_atomic_load(cnt + 64 * u.pm, __ATOMIC_RELAXED, __HIP_MEMORY_SCOPE_AGENT)) >= 32u) break;
;                 if (++spins > (1u << 22)) break;
;                 __builtin_amdgcn_s_sleep(2);
;             }
;             __builtin_amdgcn_fence(__ATOMIC_ACQUIRE, "agent");
;         }
.LBB0_782:
	s_or_b64 exec, exec, s[2:3]
	s_cmp_lt_u32 s79, 64
	s_cselect_b64 s[2:3], -1, 0
	s_cmp_gt_u32 s79, 63
	s_branch .LBB0_788
	s_lshl_b32 s12, s20, 6
	s_ashr_i32 s13, s12, 31
	s_lshl_b64 s[12:13], s[12:13], 2
	s_add_u32 s12, s1, s12
	s_addc_u32 s13, s14, s13
	s_waitcnt lgkmcnt(0)
	v_mov_b32_e32 v194, 0x400000
	v_mov_b32_e32 v192, 0
	s_branch .LBB0_785

;     __device__ __forceinline__ void run(const f32x4 (&v)[2][2][4][2], const Unit& u, int wr, int wc, int fr, int fq, PG8_LAS unsigned char* lds, int wid, int lane) const {
;     ...
;         asm volatile("s_waitcnt vmcnt(0) lgkmcnt(0)" ::: "memory"); __builtin_amdgcn_s_barrier(); asm volatile("" ::: "memory");
;         if (lane < 32) {
;             const float* slot = xbuf + (size_t)(u.pm * BM + row) * 4; float q = 0.f;
; #pragma unroll
;             for (int t = 0; t < 4; ++t) q += __hip_atomic_load(slot + t, __ATOMIC_RELAXED, __HIP_MEMORY_SCOPE_AGENT);
.LBB0_788:
	s_waitcnt lgkmcnt(0)
	s_barrier
	v_lshl_add_u32 v232, v193, 2, 0
	s_and_saveexec_b64 s[12:13], s[6:7]
	s_cbranch_execz .LBB0_790
	v_lshl_add_u64 v[192:193], v[214:215], 4, s[10:11]
	s_waitcnt lgkmcnt(0)
	s_mov_b32 s99, 0x100000
.Lprs_0:
	global_load_dword v194, v[192:193], off sc1
	global_load_dword v195, v[192:193], off offset:4 sc1
	global_load_dword v196, v[192:193], off offset:8 sc1
	global_load_dword v200, v[192:193], off offset:12 sc1
	s_waitcnt vmcnt(0)
	v_max3_u32 v201, v194, v195, v196
	v_max_u32_e32 v201, v201, v200
	v_cmp_eq_u32_e64 s[100:101], -1, v201
	s_sub_i32 s99, s99, 1
	s_cmp_eq_u64 s[100:101], 0
	s_cbranch_scc1 .Lprs_0_done
	s_cmp_eq_u32 s99, 0
	s_cbranch_scc1 .Lprs_0_done
	s_sleep 1
	s_branch .Lprs_0
.Lprs_0_done:


;     __device__ __forceinline__ void run(const f32x4 (&v)[2][2][4][2], const Unit& u, int wr, int wc, int fr, int fq, PG8_LAS unsigned char* lds, int wid, int lane) const {
;     ...
;             for (int t = 0; t < 4; ++t) q += __hip_atomic_load(slot + t, __ATOMIC_RELAXED, __HIP_MEMORY_SCOPE_AGENT);
;             S[row] = __builtin_amdgcn_rsqf(q * (1.0f / 1024.0f) + eps);
	v_add_f32_e32 v193, 0, v194
	v_add_f32_e32 v193, v193, v195
	v_add_f32_e32 v193, v193, v196
	v_add_f32_e32 v192, v193, v200
	v_mov_b32_e32 v193, 0x358637bd
	v_fmac_f32_e32 v193, 0x3a800000, v192
	v_rsq_f32_e32 v192, v193
	ds_write_b32 v232, v192 offset:8192

;     __device__ __forceinline__ void run(const f32x4 (&v)[2][2][4][2], const Unit& u, int wr, int wc, int fr, int fq, PG8_LAS unsigned char* lds, int wid, int lane) const {
;     ...
;             __hip_atomic_store(xbuf + ((size_t)(u.pm * BM + row) * 4 + u.pn), t, __ATOMIC_RELAXED, __HIP_MEMORY_SCOPE_AGENT);
;         }
;         asm volatile("s_waitcnt vmcnt(0)" ::: "memory");
.LBB0_808:
	s_or_b64 exec, exec, s[10:11]

;     __device__ __forceinline__ void run(const f32x4 (&v)[2][2][4][2], const Unit& u, int wr, int wc, int fr, int fq, PG8_LAS unsigned char* lds, int wid, int lane) const {
;     ...
;         if (lane == 0) __hip_atomic_fetch_add(cnt + 64 * u.pm, 1u, __ATOMIC_RELAXED, __HIP_MEMORY_SCOPE_AGENT);
	s_add_u32 s10, s86, 0x24000
	s_addc_u32 s11, s87, 0
	s_and_saveexec_b64 s[0:1], s[8:9]
	s_cbranch_execz .LBB0_811
	s_mov_b64 s[8:9], exec
	v_mbcnt_lo_u32_b32 v134, s8, 0
	v_mbcnt_hi_u32_b32 v134, s9, v134
	v_cmp_eq_u32_e32 vcc, 0, v134
	s_and_b64 s[12:13], exec, vcc
	s_mov_b64 exec, s[12:13]
	s_cbranch_execz .LBB0_811
	s_lshl_b32 s12, s20, 6
	s_ashr_i32 s13, s12, 31
	s_lshl_b64 s[12:13], s[12:13], 2
	s_add_u32 s12, s10, s12
	s_addc_u32 s13, s11, s13
	s_bcnt1_i32_b64 s8, s[8:9]
	v_mov_b32_e32 v134, 0
	s_waitcnt lgkmcnt(0)
	v_mov_b32_e32 v135, s8

;     __device__ __forceinline__ void run(const f32x4 (&v)[2][2][4][2], const Unit& u, int wr, int wc, int fr, int fq, PG8_LAS unsigned char* lds, int wid, int lane) const {
;     ...
;         if (wid == 0) {
;             unsigned spins = 0;
;             for (;;) {
;                 if ((unsigned)__builtin_amdgcn_readfirstlane(__hip_atomic_load(cnt + 64 * u.pm, __ATOMIC_RELAXED, __HIP_MEMORY_SCOPE_AGENT)) >= 32u) break;
;                 if (++spins > (1u << 22)) break;
;                 __builtin_amdgcn_s_sleep(2);
;             }
;             __builtin_amdgcn_fence(__ATOMIC_ACQUIRE, "agent");
;         }
.LBB0_811:
	s_or_b64 exec, exec, s[0:1]
	s_andn2_b64 vcc, exec, s[2:3]
	s_branch .LBB0_817
	s_lshl_b32 s0, s20, 6
	s_ashr_i32 s1, s0, 31
	s_lshl_b64 s[0:1], s[0:1], 2
	s_add_u32 s0, s10, s0
	s_addc_u32 s1, s11, s1
	s_waitcnt lgkmcnt(0)
	v_mov_b32_e32 v135, 0x400000
	v_mov_b32_e32 v134, 0
	s_branch .LBB0_814

;     __device__ __forceinline__ void run(const f32x4 (&v)[2][2][4][2], const Unit& u, int wr, int wc, int fr, int fq, PG8_LAS unsigned char* lds, int wid, int lane) const {
;     ...
;         asm volatile("s_waitcnt vmcnt(0) lgkmcnt(0)" ::: "memory"); __builtin_amdgcn_s_barrier(); asm volatile("" ::: "memory");
;         if (lane < 32) {
;             const float* slot = xbuf + (size_t)(u.pm * BM + row) * 4; float q = 0.f;
; #pragma unroll
;             for (int t = 0; t < 4; ++t) q += __hip_atomic_load(slot + t, __ATOMIC_RELAXED, __HIP_MEMORY_SCOPE_AGENT);
.LBB0_817:
	s_waitcnt lgkmcnt(0)
	s_barrier
	v_lshlrev_b64 v[150:151], 10, v[218:219]
	v_lshlrev_b64 v[148:149], 10, v[128:129]
	v_lshlrev_b64 v[146:147], 10, v[130:131]
	v_lshlrev_b64 v[144:145], 10, v[132:133]
	s_and_saveexec_b64 s[0:1], s[6:7]
	s_cbranch_execz .LBB0_819
	v_lshl_add_u64 v[128:129], v[214:215], 4, s[4:5]
	s_mov_b32 s99, 0x100000
.Lprs_1:
	global_load_dword v130, v[128:129], off sc1
	global_load_dword v131, v[128:129], off offset:4 sc1
	global_load_dword v132, v[128:129], off offset:8 sc1
	global_load_dword v140, v[128:129], off offset:12 sc1
	s_waitcnt vmcnt(0)
	v_max3_u32 v141, v130, v131, v132
	v_max_u32_e32 v141, v141, v140
	v_cmp_eq_u32_e64 s[100:101], -1, v141
	s_sub_i32 s99, s99, 1
	s_cmp_eq_u64 s[100:101], 0
	s_cbranch_scc1 .Lprs_1_done
	s_cmp_eq_u32 s99, 0
	s_cbranch_scc1 .Lprs_1_done
	s_sleep 1
	s_branch .Lprs_1
.Lprs_1_done:


;     __device__ __forceinline__ void run(const f32x4 (&v)[2][2][4][2], const Unit& u, int wr, int wc, int fr, int fq, PG8_LAS unsigned char* lds, int wid, int lane) const {
;     ...
;             for (int t = 0; t < 4; ++t) q += __hip_atomic_load(slot + t, __ATOMIC_RELAXED, __HIP_MEMORY_SCOPE_AGENT);
	v_add_f32_e32 v129, 0, v130

;     __device__ __forceinline__ void run(const f32x4 (&v)[2][2][4][2], const Unit& u, int wr, int wc, int fr, int fq, PG8_LAS unsigned char* lds, int wid, int lane) const {
;     ...
;             for (int t = 0; t < 4; ++t) q += __hip_atomic_load(slot + t, __ATOMIC_RELAXED, __HIP_MEMORY_SCOPE_AGENT);
	v_add_f32_e32 v129, v129, v131

;     __device__ __forceinline__ void run(const f32x4 (&v)[2][2][4][2], const Unit& u, int wr, int wc, int fr, int fq, PG8_LAS unsigned char* lds, int wid, int lane) const {
;     ...
;             for (int t = 0; t < 4; ++t) q += __hip_atomic_load(slot + t, __ATOMIC_RELAXED, __HIP_MEMORY_SCOPE_AGENT);
	v_add_f32_e32 v129, v129, v132

;     __device__ __forceinline__ void run(const f32x4 (&v)[2][2][4][2], const Unit& u, int wr, int wc, int fr, int fq, PG8_LAS unsigned char* lds, int wid, int lane) const {
;     ...
;             for (int t = 0; t < 4; ++t) q += __hip_atomic_load(slot + t, __ATOMIC_RELAXED, __HIP_MEMORY_SCOPE_AGENT);
;             S[row] = __builtin_amdgcn_rsqf(q * (1.0f / 1024.0f) + eps);
	v_add_f32_e32 v128, v129, v140
	v_mov_b32_e32 v129, 0x358637bd
	v_fmac_f32_e32 v129, 0x3a800000, v128
	v_rsq_f32_e32 v128, v129
	ds_write_b32 v232, v128 offset:8192

;     __device__ __forceinline__ void run(const f32x4 (&v)[2][2][4][2], const Unit& u, int wr, int wc, int fr, int fq, PG8_LAS unsigned char* lds, int wid, int lane) const {
;     ...
;             __hip_atomic_store(xbuf + ((size_t)(u.pm * BM + row) * 4 + u.pn), t, __ATOMIC_RELAXED, __HIP_MEMORY_SCOPE_AGENT);
;         }
;         asm volatile("s_waitcnt vmcnt(0)" ::: "memory");
.LBB0_1809:
	s_or_b64 exec, exec, s[8:9]

;     __device__ __forceinline__ void run(const f32x4 (&v)[2][2][4][2], const Unit& u, int wr, int wc, int fr, int fq, PG8_LAS unsigned char* lds, int wid, int lane) const {
;     ...
;         if (lane == 0) __hip_atomic_fetch_add(cnt + 64 * u.pm, 1u, __ATOMIC_RELAXED, __HIP_MEMORY_SCOPE_AGENT);
	s_add_u32 s3, s86, 0x28000
	s_addc_u32 s16, s87, 0
	v_cmp_eq_u32_e64 s[8:9], 0, v148
	s_and_saveexec_b64 s[10:11], s[8:9]
	s_cbranch_execz .LBB0_1812
	s_mov_b64 s[14:15], exec
	s_waitcnt lgkmcnt(0)
	v_mbcnt_lo_u32_b32 v129, s14, 0
	v_mbcnt_hi_u32_b32 v129, s15, v129
	v_cmp_eq_u32_e32 vcc, 0, v129
	s_and_b64 s[20:21], exec, vcc
	s_mov_b64 exec, s[20:21]
	s_cbranch_execz .LBB0_1812
	s_lshl_b32 s20, s0, 6
	s_ashr_i32 s21, s20, 31
	s_lshl_b64 s[20:21], s[20:21], 2
	s_add_u32 s20, s3, s20
	s_addc_u32 s21, s16, s21
	s_bcnt1_i32_b64 s14, s[14:15]
	v_mov_b32_e32 v129, 0
	v_mov_b32_e32 v134, s14

;     __device__ __forceinline__ void run(const f32x4 (&v)[2][2][4][2], const Unit& u, int wr, int wc, int fr, int fq, PG8_LAS unsigned char* lds, int wid, int lane) const {
;     ...
;         if (wid == 0) {
;             unsigned spins = 0;
;             for (;;) {
;                 if ((unsigned)__builtin_amdgcn_readfirstlane(__hip_atomic_load(cnt + 64 * u.pm, __ATOMIC_RELAXED, __HIP_MEMORY_SCOPE_AGENT)) >= 32u) break;
;                 if (++spins > (1u << 22)) break;
;                 __builtin_amdgcn_s_sleep(2);
;             }
;             __builtin_amdgcn_fence(__ATOMIC_ACQUIRE, "agent");
;         }
.LBB0_1812:
	s_or_b64 exec, exec, s[10:11]
	s_cmp_lt_u32 s79, 64
	s_cselect_b64 s[10:11], -1, 0
	s_cmp_gt_u32 s79, 63
	s_branch .LBB0_1818
	s_lshl_b32 s14, s0, 6
	s_ashr_i32 s15, s14, 31
	s_lshl_b64 s[14:15], s[14:15], 2
	s_add_u32 s14, s3, s14
	s_addc_u32 s15, s16, s15
	v_mov_b32_e32 v134, 0x400000
	s_waitcnt lgkmcnt(0)
	v_mov_b32_e32 v129, 0
	s_branch .LBB0_1815

;     __device__ __forceinline__ void run(const f32x4 (&v)[2][2][4][2], const Unit& u, int wr, int wc, int fr, int fq, PG8_LAS unsigned char* lds, int wid, int lane) const {
;     ...
;         asm volatile("s_waitcnt vmcnt(0) lgkmcnt(0)" ::: "memory"); __builtin_amdgcn_s_barrier(); asm volatile("" ::: "memory");
;         if (lane < 32) {
;             const float* slot = xbuf + (size_t)(u.pm * BM + row) * 4; float q = 0.f;
; #pragma unroll
;             for (int t = 0; t < 4; ++t) q += __hip_atomic_load(slot + t, __ATOMIC_RELAXED, __HIP_MEMORY_SCOPE_AGENT);
.LBB0_1818:
	s_waitcnt lgkmcnt(0)
	s_barrier
	v_lshl_add_u32 v188, v128, 2, 0
	s_and_saveexec_b64 s[14:15], s[6:7]
	s_cbranch_execz .LBB0_1820
	s_waitcnt lgkmcnt(0)
	v_lshl_add_u64 v[128:129], v[180:181], 4, s[12:13]
	s_mov_b32 s99, 0x100000
.Lprs_2:
	global_load_dword v134, v[128:129], off sc1
	global_load_dword v135, v[128:129], off offset:4 sc1
	global_load_dword v136, v[128:129], off offset:8 sc1
	global_load_dword v140, v[128:129], off offset:12 sc1
	s_waitcnt vmcnt(0)
	v_max3_u32 v141, v134, v135, v136
	v_max_u32_e32 v141, v141, v140
	v_cmp_eq_u32_e64 s[100:101], -1, v141
	s_sub_i32 s99, s99, 1
	s_cmp_eq_u64 s[100:101], 0
	s_cbranch_scc1 .Lprs_2_done
	s_cmp_eq_u32 s99, 0
	s_cbranch_scc1 .Lprs_2_done
	s_sleep 1
	s_branch .Lprs_2
.Lprs_2_done:


;     __device__ __forceinline__ void run(const f32x4 (&v)[2][2][4][2], const Unit& u, int wr, int wc, int fr, int fq, PG8_LAS unsigned char* lds, int wid, int lane) const {
;     ...
;             for (int t = 0; t < 4; ++t) q += __hip_atomic_load(slot + t, __ATOMIC_RELAXED, __HIP_MEMORY_SCOPE_AGENT);
;             S[row] = __builtin_amdgcn_rsqf(q * (1.0f / 1024.0f) + eps);
	v_add_f32_e32 v129, 0, v134
	v_add_f32_e32 v129, v129, v135
	v_add_f32_e32 v129, v129, v136
	v_add_f32_e32 v128, v129, v140
	v_mov_b32_e32 v129, 0x358637bd
	v_fmac_f32_e32 v129, 0x3a800000, v128
	v_rsq_f32_e32 v128, v129
	ds_write_b32 v188, v128 offset:8192

;     __device__ __forceinline__ void run(const f32x4 (&v)[2][2][4][2], const Unit& u, int wr, int wc, int fr, int fq, PG8_LAS unsigned char* lds, int wid, int lane) const {
;     ...
;             __hip_atomic_store(xbuf + ((size_t)(u.pm * BM + row) * 4 + u.pn), t, __ATOMIC_RELAXED, __HIP_MEMORY_SCOPE_AGENT);
;         }
;         asm volatile("s_waitcnt vmcnt(0)" ::: "memory");
.LBB0_1838:
	s_or_b64 exec, exec, s[12:13]

;     __device__ __forceinline__ void run(const f32x4 (&v)[2][2][4][2], const Unit& u, int wr, int wc, int fr, int fq, PG8_LAS unsigned char* lds, int wid, int lane) const {
;     ...
;         if (lane == 0) __hip_atomic_fetch_add(cnt + 64 * u.pm, 1u, __ATOMIC_RELAXED, __HIP_MEMORY_SCOPE_AGENT);
	s_add_u32 s1, s86, 0x2c000
	s_addc_u32 s12, s87, 0
	s_and_saveexec_b64 s[2:3], s[8:9]
	s_cbranch_execz .LBB0_1841
	s_mov_b64 s[8:9], exec
	v_mbcnt_lo_u32_b32 v134, s8, 0
	v_mbcnt_hi_u32_b32 v134, s9, v134
	v_cmp_eq_u32_e32 vcc, 0, v134
	s_and_b64 s[14:15], exec, vcc
	s_mov_b64 exec, s[14:15]
	s_cbranch_execz .LBB0_1841
	s_lshl_b32 s14, s0, 6
	s_ashr_i32 s15, s14, 31
	s_lshl_b64 s[14:15], s[14:15], 2
	s_add_u32 s14, s1, s14
	s_addc_u32 s15, s12, s15
	s_bcnt1_i32_b64 s8, s[8:9]
	v_mov_b32_e32 v134, 0
	s_waitcnt lgkmcnt(0)
	v_mov_b32_e32 v135, s8

;     __device__ __forceinline__ void run(const f32x4 (&v)[2][2][4][2], const Unit& u, int wr, int wc, int fr, int fq, PG8_LAS unsigned char* lds, int wid, int lane) const {
;     ...
;         if (wid == 0) {
;             unsigned spins = 0;
;             for (;;) {
;                 if ((unsigned)__builtin_amdgcn_readfirstlane(__hip_atomic_load(cnt + 64 * u.pm, __ATOMIC_RELAXED, __HIP_MEMORY_SCOPE_AGENT)) >= 32u) break;
;                 if (++spins > (1u << 22)) break;
;                 __builtin_amdgcn_s_sleep(2);
;             }
;             __builtin_amdgcn_fence(__ATOMIC_ACQUIRE, "agent");
;         }
.LBB0_1841:
	s_or_b64 exec, exec, s[2:3]
	s_andn2_b64 vcc, exec, s[10:11]
	s_branch .LBB0_1847
	s_lshl_b32 s2, s0, 6
	s_ashr_i32 s3, s2, 31
	s_lshl_b64 s[2:3], s[2:3], 2
	s_add_u32 s0, s1, s2
	s_addc_u32 s1, s12, s3
	s_waitcnt lgkmcnt(0)
	v_mov_b32_e32 v135, 0x400000
	v_mov_b32_e32 v134, 0
	s_branch .LBB0_1844

;     __device__ __forceinline__ void run(const f32x4 (&v)[2][2][4][2], const Unit& u, int wr, int wc, int fr, int fq, PG8_LAS unsigned char* lds, int wid, int lane) const {
;     ...
;         asm volatile("s_waitcnt vmcnt(0) lgkmcnt(0)" ::: "memory"); __builtin_amdgcn_s_barrier(); asm volatile("" ::: "memory");
;         if (lane < 32) {
;             const float* slot = xbuf + (size_t)(u.pm * BM + row) * 4; float q = 0.f;
; #pragma unroll
;             for (int t = 0; t < 4; ++t) q += __hip_atomic_load(slot + t, __ATOMIC_RELAXED, __HIP_MEMORY_SCOPE_AGENT);
.LBB0_1847:
	s_waitcnt lgkmcnt(0)
	s_barrier
	v_lshlrev_b64 v[154:155], 10, v[80:81]
	v_lshlrev_b64 v[148:149], 10, v[82:83]
	v_lshlrev_b64 v[146:147], 10, v[132:133]
	v_lshlrev_b64 v[144:145], 10, v[152:153]
	s_and_saveexec_b64 s[0:1], s[6:7]
	s_cbranch_execz .LBB0_1849
	v_lshl_add_u64 v[80:81], v[180:181], 4, s[4:5]
	s_mov_b32 s99, 0x100000
.Lprs_3:
	global_load_dword v82, v[80:81], off sc1
	global_load_dword v83, v[80:81], off offset:4 sc1
	global_load_dword v132, v[80:81], off offset:8 sc1
	global_load_dword v140, v[80:81], off offset:12 sc1
	s_waitcnt vmcnt(0)
	v_max3_u32 v141, v82, v83, v132
	v_max_u32_e32 v141, v141, v140
	v_cmp_eq_u32_e64 s[100:101], -1, v141
	s_sub_i32 s99, s99, 1
	s_cmp_eq_u64 s[100:101], 0
	s_cbranch_scc1 .Lprs_3_done
	s_cmp_eq_u32 s99, 0
	s_cbranch_scc1 .Lprs_3_done
	s_sleep 1
	s_branch .Lprs_3
.Lprs_3_done:


;     __device__ __forceinline__ void run(const f32x4 (&v)[2][2][4][2], const Unit& u, int wr, int wc, int fr, int fq, PG8_LAS unsigned char* lds, int wid, int lane) const {
;     ...
;             for (int t = 0; t < 4; ++t) q += __hip_atomic_load(slot + t, __ATOMIC_RELAXED, __HIP_MEMORY_SCOPE_AGENT);
	v_add_f32_e32 v81, 0, v82

;     __device__ __forceinline__ void run(const f32x4 (&v)[2][2][4][2], const Unit& u, int wr, int wc, int fr, int fq, PG8_LAS unsigned char* lds, int wid, int lane) const {
;     ...
;             for (int t = 0; t < 4; ++t) q += __hip_atomic_load(slot + t, __ATOMIC_RELAXED, __HIP_MEMORY_SCOPE_AGENT);
	v_add_f32_e32 v81, v81, v83

;     __device__ __forceinline__ void run(const f32x4 (&v)[2][2][4][2], const Unit& u, int wr, int wc, int fr, int fq, PG8_LAS unsigned char* lds, int wid, int lane) const {
;     ...
;             for (int t = 0; t < 4; ++t) q += __hip_atomic_load(slot + t, __ATOMIC_RELAXED, __HIP_MEMORY_SCOPE_AGENT);
	v_add_f32_e32 v81, v81, v132

;     __device__ __forceinline__ void run(const f32x4 (&v)[2][2][4][2], const Unit& u, int wr, int wc, int fr, int fq, PG8_LAS unsigned char* lds, int wid, int lane) const {
;     ...
;             for (int t = 0; t < 4; ++t) q += __hip_atomic_load(slot + t, __ATOMIC_RELAXED, __HIP_MEMORY_SCOPE_AGENT);
;             S[row] = __builtin_amdgcn_rsqf(q * (1.0f / 1024.0f) + eps);
	v_add_f32_e32 v80, v81, v140
	v_mov_b32_e32 v81, 0x358637bd
	v_fmac_f32_e32 v81, 0x3a800000, v80
	v_rsq_f32_e32 v80, v81
	ds_write_b32 v188, v80 offset:8192

;     __device__ __forceinline__ void run(const f32x4 (&v)[2][2][4][2], const Unit& u, int wr, int wc, int fr, int fq, PG8_LAS unsigned char* lds, int wid, int lane) const {
;     ...
;             __hip_atomic_store(xbuf + ((size_t)(u.pm * BM + row) * 4 + u.pn), t, __ATOMIC_RELAXED, __HIP_MEMORY_SCOPE_AGENT);
;         }
;         asm volatile("s_waitcnt vmcnt(0)" ::: "memory");
.LBB0_2483:
	s_or_b64 exec, exec, s[6:7]

;     __device__ __forceinline__ void run(const f32x4 (&v)[2][2][4][2], const Unit& u, int wr, int wc, int fr, int fq, PG8_LAS unsigned char* lds, int wid, int lane) const {
;     ...
;         if (lane == 0) __hip_atomic_fetch_add(cnt + 64 * u.pm, 1u, __ATOMIC_RELAXED, __HIP_MEMORY_SCOPE_AGENT);
	s_add_u32 s9, s86, 0x30000
	s_addc_u32 s10, s87, 0
	v_cmp_eq_u32_e32 vcc, 0, v166
	s_and_saveexec_b64 s[2:3], vcc
	s_cbranch_execz .LBB0_2486
	s_mov_b64 s[6:7], exec
	v_mbcnt_lo_u32_b32 v166, s6, 0
	v_mbcnt_hi_u32_b32 v166, s7, v166
	v_cmp_eq_u32_e32 vcc, 0, v166
	s_and_b64 s[12:13], exec, vcc
	s_mov_b64 exec, s[12:13]
	s_cbranch_execz .LBB0_2486
	s_lshl_b32 s12, s20, 6
	s_ashr_i32 s13, s12, 31
	s_lshl_b64 s[12:13], s[12:13], 2
	s_add_u32 s12, s9, s12
	s_addc_u32 s13, s10, s13
	s_bcnt1_i32_b64 s6, s[6:7]
	v_mov_b32_e32 v166, 0
	v_mov_b32_e32 v168, s6

;     __device__ __forceinline__ void run(const f32x4 (&v)[2][2][4][2], const Unit& u, int wr, int wc, int fr, int fq, PG8_LAS unsigned char* lds, int wid, int lane) const {
;     ...
;         if (wid == 0) {
;             unsigned spins = 0;
;             for (;;) {
;                 if ((unsigned)__builtin_amdgcn_readfirstlane(__hip_atomic_load(cnt + 64 * u.pm, __ATOMIC_RELAXED, __HIP_MEMORY_SCOPE_AGENT)) >= 32u) break;
;                 if (++spins > (1u << 22)) break;
;                 __builtin_amdgcn_s_sleep(2);
;             }
;             __builtin_amdgcn_fence(__ATOMIC_ACQUIRE, "agent");
;         }
.LBB0_2486:
	s_or_b64 exec, exec, s[2:3]
	s_cmp_gt_u32 s79, 63
	s_branch .LBB0_2492
	s_lshl_b32 s2, s20, 6
	s_ashr_i32 s3, s2, 31
	s_lshl_b64 s[2:3], s[2:3], 2
	s_add_u32 s2, s9, s2
	s_addc_u32 s3, s10, s3
	v_mov_b32_e32 v168, 0x400000
	v_mov_b32_e32 v166, 0
	s_branch .LBB0_2489

;     __device__ __forceinline__ void run(const f32x4 (&v)[2][2][4][2], const Unit& u, int wr, int wc, int fr, int fq, PG8_LAS unsigned char* lds, int wid, int lane) const {
;     ...
;         asm volatile("s_waitcnt vmcnt(0) lgkmcnt(0)" ::: "memory"); __builtin_amdgcn_s_barrier(); asm volatile("" ::: "memory");
;         if (lane < 32) {
;             const float* slot = xbuf + (size_t)(u.pm * BM + row) * 4; float q = 0.f;
; #pragma unroll
;             for (int t = 0; t < 4; ++t) q += __hip_atomic_load(slot + t, __ATOMIC_RELAXED, __HIP_MEMORY_SCOPE_AGENT);
.LBB0_2492:
	s_waitcnt lgkmcnt(0)
	s_barrier
	s_and_saveexec_b64 s[2:3], s[0:1]
	s_cbranch_execz .LBB0_2494
	v_lshl_add_u64 v[164:165], v[164:165], 4, s[4:5]
	s_mov_b32 s99, 0x100000
.Lprs_4:
	global_load_dword v166, v[164:165], off sc1
	global_load_dword v168, v[164:165], off offset:4 sc1
	global_load_dword v169, v[164:165], off offset:8 sc1
	global_load_dword v174, v[164:165], off offset:12 sc1
	s_waitcnt vmcnt(0)
	v_max3_u32 v175, v166, v168, v169
	v_max_u32_e32 v175, v175, v174
	v_cmp_eq_u32_e64 s[100:101], -1, v175
	s_sub_i32 s99, s99, 1
	s_cmp_eq_u64 s[100:101], 0
	s_cbranch_scc1 .Lprs_4_done
	s_cmp_eq_u32 s99, 0
	s_cbranch_scc1 .Lprs_4_done
	s_sleep 1
	s_branch .Lprs_4
.Lprs_4_done:


;     __device__ __forceinline__ void run(const f32x4 (&v)[2][2][4][2], const Unit& u, int wr, int wc, int fr, int fq, PG8_LAS unsigned char* lds, int wid, int lane) const {
;     ...
;             for (int t = 0; t < 4; ++t) q += __hip_atomic_load(slot + t, __ATOMIC_RELAXED, __HIP_MEMORY_SCOPE_AGENT);
;             S[row] = __builtin_amdgcn_rsqf(q * (1.0f / 1024.0f) + eps);
	v_add_f32_e32 v165, 0, v166
	v_add_f32_e32 v165, v165, v168
	v_add_f32_e32 v165, v165, v169
	v_add_f32_e32 v164, v165, v174
	v_mov_b32_e32 v165, 0x358637bd
	v_fmac_f32_e32 v165, 0x3a800000, v164
	v_rsq_f32_e32 v164, v165
	v_lshl_add_u32 v165, v167, 2, 0
	ds_write_b32 v165, v164 offset:8192
